# MLA dense attention: the rotary-key (K2) tile staging (1 global load + 1 LDS store per key tile) moves from waves 0-3 to the prioritised waves 4-7, balancing the two wave classes that share each SIMD
# speedup vs baseline: 1.0021x; 1.0021x over previous
; __device__ __forceinline__ unsigned pk2(float lo, float hi) { f32x2 v = {lo, hi}; bf16x2_t b = __builtin_convertvector(v, bf16x2_t); return __builtin_bit_cast(unsigned, b); }
; __device__ __forceinline__ void attn_unit_c(LAS unsigned char* lds, const AU& u, int tid, int wid, int lane) {
;     ...
;     const int skey = tid >> 3, sch = tid & 7, skey2 = tid >> 2, sch2 = tid & 3;
;     u32x4 kreg, vreg, k2reg = {0u, 0u, 0u, 0u};
;     const bf16_t* kp1 = u.K1 + (size_t)skey * u.k1pitch + 8 * sch;
;     const bf16_t* vp1 = u.V + (size_t)skey * u.vpitch + 8 * sch;
;     const bf16_t* kp2 = u.K2 + (size_t)skey2 * u.k2pitch + 8 * sch2;
; __device__ __forceinline__ void attn_unit_w(LAS unsigned char* lds, const AU& u, int tid, int wid, int lane) {
;     ...
;     {
;         int qidx2 = u.q0 + 32 * wid + r; asm volatile("" : "+v"(qidx2));
;         const float inv = 1.f / l;
;         bf16_t* op = u.O + (size_t)qidx2 * u.opitch + 4 * h;
; #pragma unroll
;         for (int g = 0; g < 4; ++g) {
;             u32x2 w0, w1;
;             w0.x = pk2(o0[4 * g] * inv, o0[4 * g + 1] * inv); w0.y = pk2(o0[4 * g + 2] * inv, o0[4 * g + 3] * inv);
;             w1.x = pk2(o1[4 * g] * inv, o1[4 * g + 1] * inv); w1.y = pk2(o1[4 * g + 2] * inv, o1[4 * g + 3] * inv);
;             *(u32x2*)(op + 8 * g) = w0; *(u32x2*)(op + 32 + 8 * g) = w1;
;         }
;         if (u.LSE && h == 0) u.LSE[(size_t)qidx2 * u.lsepitch] = m + __builtin_amdgcn_logf(l);
;     }
;     __syncthreads();
.LBB0_797:
	s_andn2_b64 vcc, exec, s[94:95]
	s_cbranch_vccnz .LBB0_863
	s_waitcnt lgkmcnt(0)
	s_add_u32 s23, s14, 0x600000
	s_addc_u32 s40, s15, 0
	s_add_u32 s41, s14, 0x601010
	s_addc_u32 s42, s15, 0
	s_add_u32 s43, s14, 0x2400000
	s_addc_u32 s44, s15, 0
	s_add_u32 s45, s14, 0x16400000
	s_addc_u32 s46, s15, 0
	s_add_u32 s47, s14, 0x1a400000
	s_addc_u32 s48, s15, 0
	s_add_u32 s49, s14, 0x1d600000
	s_addc_u32 s50, s15, 0
	v_and_b32_e32 v8, 16, v171
	v_lshlrev_b32_e32 v12, 2, v171
	s_add_u32 s51, s14, 0xb400000
	v_bfe_u32 v3, v171, 5, 1
	v_and_or_b32 v8, v12, 12, v8
	s_addc_u32 s56, s15, 0
	v_and_b32_e32 v6, 7, v171
	v_lshlrev_b32_e32 v172, 2, v3
	v_lshrrev_b32_e32 v7, 2, v171
	v_lshlrev_b32_e32 v200, 1, v8
	v_ashrrev_i32_e32 v8, 2, v171
	v_and_b32_e32 v1, 63, v171
	s_add_u32 s57, s14, 0xc400000
	v_lshlrev_b32_e32 v4, 3, v6
	v_lshlrev_b32_e32 v174, 4, v6
	v_and_or_b32 v6, v7, 3, v172
	v_ashrrev_i32_e32 v9, 31, v8
	s_addc_u32 s61, s15, 0
	s_lshl_b32 s65, s0, 5
	s_mulk_i32 s0, 0x3000
	v_mul_u32_u24_e32 v201, 0xc0, v6
	v_cmp_gt_u32_e64 s[8:9], 32, v1
	v_ashrrev_i32_e32 v6, 3, v171
	v_lshlrev_b64 v[176:177], 6, v[8:9]
	v_lshlrev_b32_e32 v1, 4, v171
	s_add_i32 s0, s0, 0
	v_ashrrev_i32_e32 v7, 31, v6
	v_lshl_add_u64 v[10:11], s[14:15], 0, v[176:177]
	v_and_b32_e32 v112, 48, v1
	v_add_u32_e32 v13, s0, v174
	v_add_u32_e32 v14, s0, v200
	v_lshl_add_u64 v[10:11], v[10:11], 0, v[112:113]
	s_mov_b64 s[0:1], 0x1d400000
	v_lshlrev_b64 v[180:181], 7, v[6:7]
	v_lshl_add_u64 v[178:179], v[10:11], 0, s[0:1]
	v_lshl_add_u64 v[10:11], s[14:15], 0, v[180:181]
	v_mov_b32_e32 v175, v113
	v_lshl_add_u64 v[10:11], v[10:11], 0, v[174:175]
	s_mov_b64 s[0:1], 0x3c00000
	v_lshl_add_u64 v[182:183], v[10:11], 0, s[0:1]
	s_mov_b64 s[0:1], 0x4c00000
	v_lshl_add_u64 v[184:185], v[10:11], 0, s[0:1]
	s_movk_i32 s0, 0x100
	v_cmp_gt_i32_e64 s[10:11], s0, v171
	s_movk_i32 s0, 0xd0
	v_mul_lo_u32 v1, v6, s0
	v_add_u32_e32 v175, 0, v1
	v_lshlrev_b32_e32 v1, 4, v6
	v_and_b32_e32 v173, 31, v171
	v_sub_u32_e32 v1, v175, v1
	v_bfe_u32 v5, v171, 3, 3
	v_mul_lo_u32 v203, v6, s71
	v_add_u32_e32 v204, v1, v174
	v_mul_lo_u32 v1, v8, s0
	v_mad_u32_u24 v6, v173, s0, 0
	s_add_i32 s0, 0, 0x20400
	v_readlane_b32 s4, v255, 30
	v_lshlrev_b32_e32 v170, 3, v3
	v_lshlrev_b32_e32 v0, 6, v173
	v_lshlrev_b32_e32 v2, 6, v5
	v_mul_u32_u24_e32 v5, 0xc0, v5
	v_add_u32_e32 v1, 0, v1
	v_lshlrev_b32_e32 v3, 4, v3
	v_add_u32_e32 v206, s0, v12
	v_readlane_b32 s0, v255, 24
	s_lshl_b32 s64, s4, 2
	v_or_b32_e32 v202, s65, v173
	v_add3_u32 v205, 0, v201, v200
	v_add_u32_e32 v207, s0, v3
	v_or_b32_e32 v180, v180, v174
	v_or_b32_e32 v176, v176, v112
	v_and_b32_e32 v186, 63, v171
	v_lshlrev_b32_e32 v186, 4, v186
	v_lshlrev_b32_e32 v188, 1, v2
	v_lshlrev_b32_e32 v190, 1, v4
	v_add_u32_e32 v208, v13, v5
	v_add_u32_e32 v209, v14, v201
	v_add_u32_e32 v210, v1, v112
	v_add_u32_e32 v211, v6, v3
	s_mov_b32 s74, s2
	v_readlane_b32 s5, v255, 31
	s_not_b64 s[10:11], s[10:11]
	s_cmp_lt_u32 s65, 128
	s_cbranch_scc1 .Lk2_skip
	v_add_co_u32_e32 v178, vcc, 0xfffff000, v178
	s_nop 1
	v_addc_co_u32_e32 v179, vcc, -1, v179, vcc
	v_add_u32_e32 v210, 0xffffcc00, v210
	v_add_u32_e32 v176, 0xfffff000, v176
.Lk2_skip:
	s_branch .LBB0_801
.LBB0_799:
	s_lshl_b64 s[0:1], s[30:31], 11
	s_add_u32 s0, s45, s0
	s_addc_u32 s1, s46, s1
	s_lshl_b32 s4, s75, 7
	s_add_u32 s0, s0, s4
	v_div_scale_f32 v32, s[4:5], v165, v165, 1.0
	v_rcp_f32_e32 v33, v32
	s_addc_u32 s1, s1, 0
	v_lshlrev_b32_e32 v112, 2, v172
	v_fma_f32 v34, -v32, v33, 1.0
	v_fmac_f32_e32 v33, v34, v33
	v_div_scale_f32 v34, vcc, 1.0, v165, 1.0
	v_mul_f32_e32 v35, v34, v33
	v_fma_f32 v36, -v32, v35, v34
	v_fmac_f32_e32 v35, v36, v33
	v_fma_f32 v32, -v32, v35, v34
	v_div_fmas_f32 v32, v32, v33, v35
	v_div_fixup_f32 v32, v32, v165, 1.0
	v_lshlrev_b64 v[34:35], 11, v[152:153]
	v_lshl_add_u64 v[34:35], s[0:1], 0, v[34:35]
	v_lshl_add_u64 v[34:35], v[34:35], 0, v[112:113]
	v_pk_mul_f32 v[0:1], v[0:1], v[32:33] op_sel_hi:[1,0]
	v_pk_mul_f32 v[2:3], v[2:3], v[32:33] op_sel_hi:[1,0]
	v_pk_mul_f32 v[4:5], v[4:5], v[32:33] op_sel_hi:[1,0]
	v_pk_mul_f32 v[6:7], v[6:7], v[32:33] op_sel_hi:[1,0]
	v_cvt_pk_bf16_f32 v0, v0, v1
	v_cvt_pk_bf16_f32 v1, v2, v3
	v_cvt_pk_bf16_f32 v2, v4, v5
	v_cvt_pk_bf16_f32 v3, v6, v7
	v_pk_mul_f32 v[8:9], v[8:9], v[32:33] op_sel_hi:[1,0]
	v_pk_mul_f32 v[10:11], v[10:11], v[32:33] op_sel_hi:[1,0]
	v_pk_mul_f32 v[12:13], v[12:13], v[32:33] op_sel_hi:[1,0]
	v_pk_mul_f32 v[14:15], v[14:15], v[32:33] op_sel_hi:[1,0]
	v_cvt_pk_bf16_f32 v8, v8, v9
	v_cvt_pk_bf16_f32 v9, v10, v11
	v_cvt_pk_bf16_f32 v10, v12, v13
	v_cvt_pk_bf16_f32 v11, v14, v15
	v_pk_mul_f32 v[16:17], v[16:17], v[32:33] op_sel_hi:[1,0]
	v_pk_mul_f32 v[18:19], v[18:19], v[32:33] op_sel_hi:[1,0]
	v_pk_mul_f32 v[20:21], v[20:21], v[32:33] op_sel_hi:[1,0]
	v_pk_mul_f32 v[22:23], v[22:23], v[32:33] op_sel_hi:[1,0]
	v_cvt_pk_bf16_f32 v16, v16, v17
	v_cvt_pk_bf16_f32 v17, v18, v19
	v_cvt_pk_bf16_f32 v18, v20, v21
	v_cvt_pk_bf16_f32 v19, v22, v23
	v_pk_mul_f32 v[24:25], v[24:25], v[32:33] op_sel_hi:[1,0]
	v_pk_mul_f32 v[26:27], v[26:27], v[32:33] op_sel_hi:[1,0]
	v_pk_mul_f32 v[28:29], v[28:29], v[32:33] op_sel_hi:[1,0]
	v_pk_mul_f32 v[30:31], v[30:31], v[32:33] op_sel_hi:[1,0]
	v_cvt_pk_bf16_f32 v24, v24, v25
	v_cvt_pk_bf16_f32 v25, v26, v27
	v_cvt_pk_bf16_f32 v26, v28, v29
	v_cvt_pk_bf16_f32 v27, v30, v31
	s_nop 1
	v_permlane32_swap_b32_e32 v0, v2
	v_permlane32_swap_b32_e32 v1, v3
	v_permlane32_swap_b32_e32 v8, v10
	v_permlane32_swap_b32_e32 v9, v11
	v_permlane32_swap_b32_e32 v16, v18
	v_permlane32_swap_b32_e32 v17, v19
	v_permlane32_swap_b32_e32 v24, v26
	v_permlane32_swap_b32_e32 v25, v27
	global_store_dwordx4 v[34:35], v[0:3], off offset:1024
	global_store_dwordx4 v[34:35], v[8:11], off offset:1056
	global_store_dwordx4 v[34:35], v[16:19], off offset:1088
	global_store_dwordx4 v[34:35], v[24:27], off offset:1120
	s_barrier
